# v81 + layer-3 pooling layer without grid barriers: pool-elem items remapped to the owning row panel, MLP-down(L2)->pool-elem(L3)->pool GEMM(L3) as 3-panel hand-offs
# speedup vs baseline: 1.0062x; 1.0062x over previous
; __global__ void __launch_bounds__(NWAVES * 64, 2) fwd_kernel(Args args) {
;     ...
;                 const int nitems = (nrows / 64) * 4;
;                 f32x4 pv[10]; float rreg;
;     ...
;                 { const int it0_ = bx < nitems ? bx : 0; PL_PREFETCH(it0_); }
.LBB0_1174:
	s_andn2_b64 vcc, exec, s[0:1]
	s_movk_i32 s30, 0x1fff
	s_movk_i32 s44, 0xff00
	s_cbranch_vccnz .LBB0_1372
	v_readlane_b32 s0, v255, 8
	v_readlane_b32 s1, v255, 9
	s_mov_b32 s2, s0
	s_cmp_lg_u32 s0, 0
	s_cselect_b64 s[0:1], -1, 0
	s_cmp_eq_u32 s2, 0
	s_movk_i32 s2, 0x420
	s_cselect_b32 s4, s2, 0x400
	s_waitcnt vmcnt(0)
	v_mov_b32_e32 v42, v215
	s_mov_b32 s23, s84
	s_mov_b32 s5, s82
	v_readlane_b32 s100, v255, 8
	s_cmp_lg_u32 s100, 3
	s_cbranch_scc1 .Lpe_noremap
	s_and_b32 s100, s84, 7
	s_lshl_b32 s100, s100, 3
	s_bfe_u32 s101, s84, 0x30003
	s_add_i32 s100, s100, s101
	s_lshl_b32 s100, s100, 4
	s_lshr_b32 s101, s84, 6
	s_add_i32 s23, s100, s101
	s_mov_b32 s5, 4
	s_add_i32 s4, s23, 16
.Lpe_noremap:
	s_cmp_lt_i32 s23, s4
	s_waitcnt lgkmcnt(0)
	s_cselect_b64 s[6:7], -1, 0
	s_and_b64 s[12:13], s[6:7], exec
	s_cselect_b32 s8, s23, 0
	s_lshl_b32 s12, s8, 4
	s_and_b32 s14, s12, 0xffffffc0
	s_cmpk_lt_i32 s14, 0x4000
	s_cselect_b32 s13, 0xffffe000, s44
	s_cselect_b32 s15, s30, 0xff
	s_and_b32 s19, s13, s12
	s_sub_i32 s17, s14, s19
	s_add_i32 s20, s17, -8
	v_ashrrev_i32_e32 v65, 6, v42
	v_lshlrev_b32_e32 v0, 2, v42
	v_add_u32_e32 v43, s20, v65
	v_and_b32_e32 v2, 0xfc, v0
	v_min_i32_e32 v0, s15, v43
	v_cmp_lt_i32_e32 vcc, -1, v43
	s_lshl_b32 s8, s8, 8
	s_mov_b64 s[2:3], s[94:95]
	v_cndmask_b32_e32 v44, 0, v0, vcc
	v_add_u32_e32 v0, s19, v44
	s_and_b32 s18, s8, 0x300
	s_mov_b64 s[12:13], -1
	s_and_b64 vcc, exec, s[0:1]
	v_ashrrev_i32_e32 v1, 31, v0
	v_lshlrev_b32_e32 v60, 1, v2
	s_cbranch_vccz .LBB0_1177
	s_load_dwordx2 s[12:13], s[2:3], 0xb8
	v_lshlrev_b64 v[4:5], 11, v[0:1]
	s_lshl_b32 s8, s18, 1
	v_mov_b32_e32 v61, v213
	s_waitcnt lgkmcnt(0)
	v_lshl_add_u64 v[4:5], s[12:13], 0, v[4:5]
	v_lshl_add_u64 v[4:5], v[4:5], 0, s[8:9]
	v_lshl_add_u64 v[4:5], v[4:5], 0, v[60:61]
	v_add_co_u32_e32 v4, vcc, 0x14200000, v4
	s_mov_b64 s[12:13], 0
	s_nop 0
	v_addc_co_u32_e32 v5, vcc, 0, v5, vcc
	global_load_dwordx2 v[4:5], v[4:5], off
	s_waitcnt vmcnt(0)
	v_lshlrev_b32_e32 v36, 16, v4
	v_and_b32_e32 v37, 0xffff0000, v4
	v_lshlrev_b32_e32 v38, 16, v5
	v_and_b32_e32 v39, 0xffff0000, v5

.LBB0_1289:
	v_readlane_b32 s0, v254, 2
	s_add_i32 s4, s0, 1
	s_cmp_lt_i32 s4, s81
	s_cbranch_scc0 .LBB0_1372
	v_readlane_b32 s100, v255, 8
	s_cmp_eq_u32 s100, 3
	s_cbranch_scc0 .Lp3_orig_2
	s_waitcnt vmcnt(0) lgkmcnt(0)
	s_barrier
	v_readlane_b32 s100, v255, 59
	s_add_i32 s100, s100, 1
	v_writelane_b32 v255, s100, 59
	v_cmp_eq_u32_e32 vcc, 0, v215
	s_and_saveexec_b64 s[0:1], vcc
	s_cbranch_execz .Lp3_w_2
	s_load_dwordx2 s[2:3], s[94:95], 0xb8
	s_lshl_b32 s100, s100, 2
	v_readlane_b32 s101, v255, 12
	s_and_b32 s6, s101, 63
	s_lshl_b32 s6, s6, 6
	s_cmp_lt_u32 s6, 0x800
	s_movk_i32 s7, 0x1400
	s_cselect_b32 s7, 0xc00, s7
	s_add_i32 s6, s6, s7
	v_mov_b32_e32 v0, s6
	v_mov_b32_e32 v1, 1
	s_and_b32 s6, s101, 7
	s_lshl_b32 s6, s6, 3
	s_bfe_u32 s7, s101, 0x30003
	s_add_i32 s101, s6, s7
	s_sub_i32 s6, s101, 1
	s_max_i32 s6, s6, 0
	s_lshr_b32 s7, s6, 3
	s_and_b32 s6, s6, 7
	s_lshl_b32 s6, s6, 3
	s_add_i32 s6, s6, s7
	s_lshl_b32 s6, s6, 6
	s_cmp_lt_u32 s6, 0x800
	s_movk_i32 s7, 0x1400
	s_cselect_b32 s7, 0xc00, s7
	s_add_i32 s6, s6, s7
	v_mov_b32_e32 v3, s6
	s_add_i32 s6, s101, 1
	s_min_i32 s6, s6, 63
	s_lshr_b32 s7, s6, 3
	s_and_b32 s6, s6, 7
	s_lshl_b32 s6, s6, 3
	s_add_i32 s6, s6, s7
	s_lshl_b32 s6, s6, 6
	s_cmp_lt_u32 s6, 0x800
	s_movk_i32 s7, 0x1400
	s_cselect_b32 s7, 0xc00, s7
	s_add_i32 s6, s6, s7
	v_mov_b32_e32 v4, s6
	s_waitcnt lgkmcnt(0)
	s_add_u32 s2, s2, 0xe0000
	s_addc_u32 s3, s3, 0
	global_atomic_add v0, v1, s[2:3]
	buffer_inv sc1
	s_mov_b32 s6, 0

.Lp3_d0_2:
	s_mov_b32 s6, 0
.Lp3_p1_2:
	global_load_dword v2, v3, s[2:3] sc1
	s_waitcnt vmcnt(0)
	v_cmp_le_u32_e32 vcc, s100, v2
	s_cbranch_vccnz .Lp3_d1_2
	s_sleep 1
	s_add_i32 s6, s6, 1
	s_cmp_lt_u32 s6, 0x100000
	s_cbranch_scc1 .Lp3_p1_2

.Lp3_p2_2:
	global_load_dword v2, v4, s[2:3] sc1
	s_waitcnt vmcnt(0)
	v_cmp_le_u32_e32 vcc, s100, v2
	s_cbranch_vccnz .Lp3_d2_2
	s_sleep 1
	s_add_i32 s6, s6, 1
	s_cmp_lt_u32 s6, 0x100000
	s_cbranch_scc1 .Lp3_p2_2

; __device__ __forceinline__ unsigned xb_add(unsigned* p, unsigned v) { return __hip_atomic_fetch_add(p, v, __ATOMIC_RELAXED, __HIP_MEMORY_SCOPE_AGENT); }
; __device__ __forceinline__ void xcd_barrier(const XcdBarrier& b, int tid) {
;     asm volatile("s_waitcnt vmcnt(0)" ::: "memory");
;     __syncthreads();
;     if (tid == 0) {
;         unsigned* bar = b.bar;
;         __builtin_amdgcn_s_waitcnt(0);
;         unsigned nloc = b.st[0], nx = b.st[1];
;         if (nloc == 0u) { xcd_barrier_complete(bar, b.x, nloc, nx); b.st[0] = nloc; b.st[1] = nx; }
;         const unsigned old = xb_add(&bar[XB_XSUB(b.x)], 1u);
.Lp3_orig_2:
	v_readlane_b32 s0, v254, 3
	v_readlane_b32 s1, v254, 4
	s_andn2_b64 vcc, exec, s[0:1]
	s_cbranch_vccnz .LBB0_1302
	s_barrier
	s_mov_b64 s[0:1], exec
	v_readlane_b32 s2, v255, 6
	v_readlane_b32 s3, v255, 7
	s_and_b64 s[2:3], s[0:1], s[2:3]
	s_mov_b64 exec, s[2:3]
	s_cbranch_execz .LBB0_1301
	v_readlane_b32 s2, v254, 0
	v_readlane_b32 s3, v254, 1
	buffer_wbl2 sc1
	s_waitcnt vmcnt(0)
	s_load_dwordx2 s[2:3], s[2:3], 0x58
	s_mov_b64 s[6:7], exec
	v_mbcnt_lo_u32_b32 v1, s6, 0
	v_mbcnt_hi_u32_b32 v1, s7, v1
	v_cmp_eq_u32_e32 vcc, 0, v1
	s_waitcnt lgkmcnt(0)
	global_load_dword v0, v213, s[2:3] offset:40
	s_and_saveexec_b64 s[12:13], vcc
	s_cbranch_execz .LBB0_1294
	s_bcnt1_i32_b64 s5, s[6:7]
	v_mov_b32_e32 v2, s5
	global_atomic_add v2, v213, v2, s[2:3] offset:32 sc0

.Lgs_orig_5:
	v_readlane_b32 s100, v255, 8
	s_cmp_eq_u32 s100, 2
	s_cbranch_scc0 .Lp3_orig_1
	s_waitcnt vmcnt(0) lgkmcnt(0)
	s_barrier
	v_readlane_b32 s100, v255, 59
	s_add_i32 s100, s100, 1
	v_writelane_b32 v255, s100, 59
	v_cmp_eq_u32_e32 vcc, 0, v215
	s_and_saveexec_b64 s[0:1], vcc
	s_cbranch_execz .Lp3_w_1
	s_load_dwordx2 s[2:3], s[94:95], 0xb8
	s_lshl_b32 s100, s100, 2
	v_readlane_b32 s101, v255, 12
	s_and_b32 s6, s101, 63
	s_lshl_b32 s6, s6, 6
	s_cmp_lt_u32 s6, 0x800
	s_movk_i32 s7, 0x1400
	s_cselect_b32 s7, 0xc00, s7
	s_add_i32 s6, s6, s7
	v_mov_b32_e32 v0, s6
	v_mov_b32_e32 v1, 1
	s_and_b32 s6, s101, 7
	s_lshl_b32 s6, s6, 3
	s_bfe_u32 s7, s101, 0x30003
	s_add_i32 s101, s6, s7
	s_sub_i32 s6, s101, 1
	s_max_i32 s6, s6, 0
	s_lshr_b32 s7, s6, 3
	s_and_b32 s6, s6, 7
	s_lshl_b32 s6, s6, 3
	s_add_i32 s6, s6, s7
	s_lshl_b32 s6, s6, 6
	s_cmp_lt_u32 s6, 0x800
	s_movk_i32 s7, 0x1400
	s_cselect_b32 s7, 0xc00, s7
	s_add_i32 s6, s6, s7
	v_mov_b32_e32 v3, s6
	s_add_i32 s6, s101, 1
	s_min_i32 s6, s6, 63
	s_lshr_b32 s7, s6, 3
	s_and_b32 s6, s6, 7
	s_lshl_b32 s6, s6, 3
	s_add_i32 s6, s6, s7
	s_lshl_b32 s6, s6, 6
	s_cmp_lt_u32 s6, 0x800
	s_movk_i32 s7, 0x1400
	s_cselect_b32 s7, 0xc00, s7
	s_add_i32 s6, s6, s7
	v_mov_b32_e32 v4, s6
	s_waitcnt lgkmcnt(0)
	s_add_u32 s2, s2, 0xe0000
	s_addc_u32 s3, s3, 0
	global_atomic_add v0, v1, s[2:3]
	buffer_inv sc1
	s_mov_b32 s6, 0
